# SEAM(5)/(7): XCD leader's L2 write-back skipped when the census shows blockIdx%8 == XCD for every workgroup (all later hand-offs are XCD-local)
# speedup vs baseline: 1.0006x; 1.0006x over previous
; #define LAS __attribute__((address_space(3)))
; __global__ void __launch_bounds__(512, 2) hybrid_fwd(Args args) {
;     ...
;     if (IN(0) && IN(1) && G == 256) {
;         LAS unsigned* gl = (LAS unsigned*)(lds + 131072 + 512);
;         if (tid < 64) { const unsigned a = __hip_atomic_load(xcctab + tid, __ATOMIC_RELAXED, __HIP_MEMORY_SCOPE_AGENT), b2 = __hip_atomic_load(xcctab + tid + 64, __ATOMIC_RELAXED, __HIP_MEMORY_SCOPE_AGENT),
;                                            c2 = __hip_atomic_load(xcctab + tid + 128, __ATOMIC_RELAXED, __HIP_MEMORY_SCOPE_AGENT), d2 = __hip_atomic_load(xcctab + tid + 192, __ATOMIC_RELAXED, __HIP_MEMORY_SCOPE_AGENT);
;             const bool okg = (a != 0u) && a == b2 && a == c2 && a == d2;
;             const unsigned long long m = __ballot(okg);
;             if (tid == 0) gl[0] = (m == ~0ull) ? 1u : 0u; }
;         __syncthreads();
;         grp_local = gl[0] != 0u;
;     }
.LBB0_116:
	s_cmpk_eq_i32 s42, 0x100
	s_cselect_b64 s[8:9], -1, 0
	s_and_b64 s[0:1], s[0:1], s[8:9]
	s_andn2_b64 vcc, exec, s[0:1]
	s_mov_b64 s[10:11], 0
	s_cbranch_vccnz .LBB0_121
	v_cmp_gt_u32_e32 vcc, 64, v226
	s_and_saveexec_b64 s[10:11], vcc
	s_cbranch_execz .LBB0_120
	v_and_b32_e32 v4, 7, v226
	v_lshlrev_b32_e32 v4, 2, v4
	global_load_dword v4, v4, s[96:97] sc1
	v_lshlrev_b32_e32 v0, 2, v226
	global_load_dword v1, v0, s[96:97] sc1
	global_load_dword v2, v0, s[96:97] offset:256 sc1
	global_load_dword v3, v0, s[96:97] offset:512 sc1
	s_nop 0
	global_load_dword v0, v0, s[96:97] offset:768 sc1
	s_waitcnt vmcnt(3)
	v_cmp_ne_u32_e32 vcc, 0, v1
	s_waitcnt vmcnt(2)
	v_cmp_eq_u32_e64 s[0:1], v1, v2
	s_waitcnt vmcnt(1)
	v_cmp_eq_u32_e64 s[4:5], v1, v3
	s_and_b64 s[0:1], s[0:1], s[4:5]
	s_waitcnt vmcnt(0)
	v_cmp_eq_u32_e64 s[6:7], v1, v0
	s_and_b64 s[0:1], s[0:1], vcc
	s_and_b64 s[0:1], s[0:1], s[6:7]
	v_cmp_eq_u32_e64 s[4:5], v1, v4
	s_nop 1
	s_and_b64 s[0:1], s[0:1], s[4:5]
	v_cndmask_b32_e64 v0, 0, 1, s[0:1]
	v_readlane_b32 s0, v252, 3
	v_cmp_ne_u32_e32 vcc, 0, v0
	v_readlane_b32 s1, v252, 4
	s_and_b64 exec, exec, s[0:1]
	s_cbranch_execz .LBB0_120
	s_cmp_eq_u64 vcc, -1
	s_cselect_b64 s[0:1], -1, 0
	v_cndmask_b32_e64 v0, 0, 1, s[0:1]
	s_add_i32 s0, 0, 0x20200
	v_mov_b32_e32 v1, s0
	ds_write_b32 v1, v0

; __device__ __forceinline__ unsigned xb_add(unsigned* p, unsigned v) { return __hip_atomic_fetch_add(p, v, __ATOMIC_RELAXED, __HIP_MEMORY_SCOPE_AGENT); }
; __device__ __forceinline__ void xcd_barrier(const XcdBarrier& b) {
;     ...
;         if (old + 1u == (gen + 1u) * nloc) {
;             __builtin_amdgcn_fence(__ATOMIC_RELEASE, "agent");
;             asm volatile("s_waitcnt vmcnt(0)" ::: "memory");
;             const unsigned og = xb_add(&bar[XB_TOP], 1u);
;             const unsigned tg = og / nx;
;             if (og + 1u == (tg + 1u) * nx) xb_add(&bar[XB_TOPGEN], 1u);
.LBB0_612:
	s_andn2_saveexec_b64 s[8:9], s[8:9]
	s_cbranch_execz .LBB0_632
	s_mov_b64 s[8:9], exec
	v_mov_b32_e32 v2, 0x20200
	ds_read_b32 v2, v2
	s_waitcnt lgkmcnt(0)
	v_cmp_ne_u32_e32 vcc, 0, v2
	s_cbranch_vccnz .Lwbskip6
	buffer_wbl2 sc1
.Lwbskip6:
	s_waitcnt lgkmcnt(0)
	s_waitcnt vmcnt(0)
	v_mbcnt_lo_u32_b32 v1, s8, 0
	v_mbcnt_hi_u32_b32 v1, s9, v1
	v_cmp_eq_u32_e32 vcc, 0, v1
	s_and_saveexec_b64 s[10:11], vcc
	s_cbranch_execz .LBB0_615
	s_bcnt1_i32_b64 s8, s[8:9]
	v_mov_b32_e32 v2, 0x7000
	v_mov_b32_e32 v3, s8
	global_atomic_add v2, v2, v3, s[86:87] offset:1024 sc0

; __device__ __forceinline__ unsigned xb_add(unsigned* p, unsigned v) { return __hip_atomic_fetch_add(p, v, __ATOMIC_RELAXED, __HIP_MEMORY_SCOPE_AGENT); }
; __device__ __forceinline__ void xcd_barrier(const XcdBarrier& b) {
;     ...
;         if (old + 1u == (gen + 1u) * nloc) {
;             __builtin_amdgcn_fence(__ATOMIC_RELEASE, "agent");
;             asm volatile("s_waitcnt vmcnt(0)" ::: "memory");
;             const unsigned og = xb_add(&bar[XB_TOP], 1u);
;             const unsigned tg = og / nx;
;             if (og + 1u == (tg + 1u) * nx) xb_add(&bar[XB_TOPGEN], 1u);
.LBB0_864:
	s_andn2_saveexec_b64 s[12:13], s[12:13]
	s_cbranch_execz .LBB0_884
	s_mov_b64 s[12:13], exec
	v_mov_b32_e32 v2, 0x20200
	ds_read_b32 v2, v2
	s_waitcnt lgkmcnt(0)
	v_cmp_ne_u32_e32 vcc, 0, v2
	s_cbranch_vccnz .Lwbskip8
	buffer_wbl2 sc1
.Lwbskip8:
	s_waitcnt lgkmcnt(0)
	s_waitcnt vmcnt(0)
	v_mbcnt_lo_u32_b32 v1, s12, 0
	v_mbcnt_hi_u32_b32 v1, s13, v1
	v_cmp_eq_u32_e32 vcc, 0, v1
	s_and_saveexec_b64 s[14:15], vcc
	s_cbranch_execz .LBB0_867
	s_bcnt1_i32_b64 s3, s[12:13]
	v_mov_b32_e32 v2, 0x7000
	v_mov_b32_e32 v3, s3
	global_atomic_add v2, v2, v3, s[86:87] offset:1024 sc0
